# v11 plus FoX QK/PV fragment LDS reads issued ahead with counted lgkmcnt
# speedup vs baseline: 1.0011x; 1.0011x over previous
; #define LAS __attribute__((address_space(3)))
; #define PVS(s, pk) do { const bf16x8 a0_ = *(const LAS bf16x8*)(vb + (s) * 32), a1_ = *(const LAS bf16x8*)(vb + 32 * VT_STRIDE + (s) * 32); \
;             o0 = __builtin_amdgcn_mfma_f32_32x32x16_bf16(a0_, pk, o0, 0, 0, 0); o1 = __builtin_amdgcn_mfma_f32_32x32x16_bf16(a1_, pk, o1, 0, 0, 0); } while (0)
; #define PVS(s, pk) do { const bf16x8 a0_ = *(const LAS bf16x8*)(vb + (s) * 32), a1_ = *(const LAS bf16x8*)(vb + 32 * VT_STRIDE + (s) * 32); \
;             o0 = __builtin_amdgcn_mfma_f32_32x32x16_bf16(a0_, pk, o0, 0, 0, 0); o1 = __builtin_amdgcn_mfma_f32_32x32x16_bf16(a1_, pk, o1, 0, 0, 0); } while (0)
; #define PVS(s, pk) do { const bf16x8 a0_ = *(const LAS bf16x8*)(vb + (s) * 32), a1_ = *(const LAS bf16x8*)(vb + 32 * VT_STRIDE + (s) * 32); \
;             o0 = __builtin_amdgcn_mfma_f32_32x32x16_bf16(a0_, pk, o0, 0, 0, 0); o1 = __builtin_amdgcn_mfma_f32_32x32x16_bf16(a1_, pk, o1, 0, 0, 0); } while (0)
; #define PVS(s, pk) do { const bf16x8 a0_ = *(const LAS bf16x8*)(vb + (s) * 32), a1_ = *(const LAS bf16x8*)(vb + 32 * VT_STRIDE + (s) * 32); \
;             o0 = __builtin_amdgcn_mfma_f32_32x32x16_bf16(a0_, pk, o0, 0, 0, 0); o1 = __builtin_amdgcn_mfma_f32_32x32x16_bf16(a1_, pk, o1, 0, 0, 0); } while (0)
; #define PVS(s, pk) do { const bf16x8 a0_ = *(const LAS bf16x8*)(vb + (s) * 32), a1_ = *(const LAS bf16x8*)(vb + 32 * VT_STRIDE + (s) * 32); \
;             o0 = __builtin_amdgcn_mfma_f32_32x32x16_bf16(a0_, pk, o0, 0, 0, 0); o1 = __builtin_amdgcn_mfma_f32_32x32x16_bf16(a1_, pk, o1, 0, 0, 0); } while (0)
; template <int MODE>
; __device__ __forceinline__ void attn_unit(LAS unsigned char* lds, const AttnArgs& A, int qb) {
;     ...
;             LAS unsigned char* kb = buf + kperm * 16 + hi * 1024;
; #pragma unroll
;             for (int d0 = 0; d0 < 4; ++d0) {
;                 const bf16x8 kf0 = *(const LAS bf16x8*)(kb + d0 * 2048), kf1 = *(const LAS bf16x8*)(kb + d0 * 2048 + 512);
;                 p0 = __builtin_amdgcn_mfma_f32_32x32x16_bf16(kf0, qr[d0], p0, 0, 0, 0);
;                 p1 = __builtin_amdgcn_mfma_f32_32x32x16_bf16(kf1, qr[d0], p1, 0, 0, 0);
;             }
;         if (prev_active) {
;             const LAS unsigned char* vb = lds + prevbuf + KB_BYTES + r32 * VT_STRIDE + hi * 16;
;     ...
;             PVS(0, pkP0); PVS(1, pkP1); PVS(2, pkP2); PVS(3, pkP3);
;     ...
;         }
.LBB0_973:
	s_andn2_b64 vcc, exec, s[28:29]
	s_cbranch_vccnz .LBB0_981
	s_nop 5
	v_add_u32_e32 v6, v186, v187
	s_and_b64 vcc, exec, s[10:11]
	ds_read_b128 v[2:5], v6
	ds_read_b128 v[8:11], v6 offset:512
	ds_read_b128 v[12:15], v6 offset:2048
	ds_read_b128 v[16:19], v6 offset:2560
	ds_read_b128 v[20:23], v6 offset:4096
	ds_read_b128 v[24:27], v6 offset:4608
	ds_read_b128 v[28:31], v6 offset:6144
	s_waitcnt lgkmcnt(6)
	v_mfma_f32_32x32x16_bf16 v[34:49], v[2:5], v[98:101], 0
	ds_read_b128 v[2:5], v6 offset:6656
	s_waitcnt lgkmcnt(6)
	v_mfma_f32_32x32x16_bf16 v[50:65], v[8:11], v[98:101], 0
	s_waitcnt lgkmcnt(5)
	v_mfma_f32_32x32x16_bf16 v[34:49], v[12:15], v[102:105], v[34:49]
	s_waitcnt lgkmcnt(4)
	v_mfma_f32_32x32x16_bf16 v[50:65], v[16:19], v[102:105], v[50:65]
	s_waitcnt lgkmcnt(3)
	v_mfma_f32_32x32x16_bf16 v[34:49], v[20:23], v[106:109], v[34:49]
	s_waitcnt lgkmcnt(2)
	v_mfma_f32_32x32x16_bf16 v[50:65], v[24:27], v[106:109], v[50:65]
	s_waitcnt lgkmcnt(1)
	v_mfma_f32_32x32x16_bf16 v[34:49], v[28:31], v[110:113], v[34:49]
	s_waitcnt lgkmcnt(0)
	v_mfma_f32_32x32x16_bf16 v[50:65], v[2:5], v[110:113], v[50:65]
	s_cbranch_vccnz .LBB0_976
	v_add_u32_e32 v6, s2, v191
	ds_read_b128 v[2:5], v6 offset:8192
	ds_read_b128 v[8:11], v6 offset:12800
	ds_read_b128 v[12:15], v6 offset:8224
	ds_read_b128 v[16:19], v6 offset:12832
	ds_read_b128 v[20:23], v6 offset:8256
	ds_read_b128 v[24:27], v6 offset:12864
	ds_read_b128 v[28:31], v6 offset:12896
	s_waitcnt lgkmcnt(6)
	v_mfma_f32_32x32x16_bf16 v[82:97], v[2:5], v[150:153], v[82:97]
	ds_read_b128 v[2:5], v6 offset:8288
	s_waitcnt lgkmcnt(6)
	v_mfma_f32_32x32x16_bf16 v[66:81], v[8:11], v[150:153], v[66:81]
	s_waitcnt lgkmcnt(5)
	v_mfma_f32_32x32x16_bf16 v[82:97], v[12:15], v[142:145], v[82:97]
	s_waitcnt lgkmcnt(4)
	v_mfma_f32_32x32x16_bf16 v[66:81], v[16:19], v[142:145], v[66:81]
	s_waitcnt lgkmcnt(3)
	v_mfma_f32_32x32x16_bf16 v[82:97], v[20:23], v[146:149], v[82:97]
	s_waitcnt lgkmcnt(2)
	v_mfma_f32_32x32x16_bf16 v[66:81], v[24:27], v[146:149], v[66:81]
	s_waitcnt lgkmcnt(1)
	v_mfma_f32_32x32x16_bf16 v[66:81], v[28:31], v[138:141], v[66:81]
	s_waitcnt lgkmcnt(0)
	v_mfma_f32_32x32x16_bf16 v[82:97], v[2:5], v[138:141], v[82:97]

; #define LAS __attribute__((address_space(3)))
; #define PVS(s, pk) do { const bf16x8 a0_ = *(const LAS bf16x8*)(vb + (s) * 32), a1_ = *(const LAS bf16x8*)(vb + 32 * VT_STRIDE + (s) * 32); \
;             o0 = __builtin_amdgcn_mfma_f32_32x32x16_bf16(a0_, pk, o0, 0, 0, 0); o1 = __builtin_amdgcn_mfma_f32_32x32x16_bf16(a1_, pk, o1, 0, 0, 0); } while (0)
; #define PVS(s, pk) do { const bf16x8 a0_ = *(const LAS bf16x8*)(vb + (s) * 32), a1_ = *(const LAS bf16x8*)(vb + 32 * VT_STRIDE + (s) * 32); \
;             o0 = __builtin_amdgcn_mfma_f32_32x32x16_bf16(a0_, pk, o0, 0, 0, 0); o1 = __builtin_amdgcn_mfma_f32_32x32x16_bf16(a1_, pk, o1, 0, 0, 0); } while (0)
; #define PVS(s, pk) do { const bf16x8 a0_ = *(const LAS bf16x8*)(vb + (s) * 32), a1_ = *(const LAS bf16x8*)(vb + 32 * VT_STRIDE + (s) * 32); \
;             o0 = __builtin_amdgcn_mfma_f32_32x32x16_bf16(a0_, pk, o0, 0, 0, 0); o1 = __builtin_amdgcn_mfma_f32_32x32x16_bf16(a1_, pk, o1, 0, 0, 0); } while (0)
; #define PVS(s, pk) do { const bf16x8 a0_ = *(const LAS bf16x8*)(vb + (s) * 32), a1_ = *(const LAS bf16x8*)(vb + 32 * VT_STRIDE + (s) * 32); \
;             o0 = __builtin_amdgcn_mfma_f32_32x32x16_bf16(a0_, pk, o0, 0, 0, 0); o1 = __builtin_amdgcn_mfma_f32_32x32x16_bf16(a1_, pk, o1, 0, 0, 0); } while (0)
; template <int MODE>
; __device__ __forceinline__ void attn_unit(LAS unsigned char* lds, const AttnArgs& A, int qb) {
;     ...
;         else if (MODE == M_MOBA) active = (i < 4) ? (key0 <= w0 + 31) : (((wmask >> ((i - 4) >> 2)) & 1ull) != 0ull);
;         else active = key0 <= w0 + 31;
;         if (active) {
;             f32x16 p0, p1;
; #pragma unroll
;             for (int r = 0; r < 16; ++r) { p0[r] = 0.f; p1[r] = 0.f; }
;             LAS unsigned char* kb = buf + kperm * 16 + hi * 1024;
; #pragma unroll
;             for (int d0 = 0; d0 < 4; ++d0) {
;                 const bf16x8 kf0 = *(const LAS bf16x8*)(kb + d0 * 2048), kf1 = *(const LAS bf16x8*)(kb + d0 * 2048 + 512);
;                 p0 = __builtin_amdgcn_mfma_f32_32x32x16_bf16(kf0, qr[d0], p0, 0, 0, 0);
;                 p1 = __builtin_amdgcn_mfma_f32_32x32x16_bf16(kf1, qr[d0], p1, 0, 0, 0);
;             }
;         if (prev_active) {
;             const LAS unsigned char* vb = lds + prevbuf + KB_BYTES + r32 * VT_STRIDE + hi * 16;
;     ...
;             PVS(0, pkP0); PVS(1, pkP1); PVS(2, pkP2); PVS(3, pkP3);
;     ...
;         }
.LBB0_997:
	s_add_i32 s80, s52, 0xffffff81
	s_cmp_le_i32 s80, s48
	s_cselect_b64 s[4:5], -1, 0
	s_cmp_gt_i32 s80, s48
	s_cbranch_scc1 .LBB0_1004
	v_add_u32_e32 v70, v186, v187
	s_andn2_b64 vcc, exec, s[26:27]
	ds_read_b128 v[66:69], v70 offset:17664
	ds_read_b128 v[74:77], v70 offset:19712
	ds_read_b128 v[78:81], v70 offset:18176
	ds_read_b128 v[82:85], v70 offset:20224
	ds_read_b128 v[86:89], v70 offset:21760
	ds_read_b128 v[90:93], v70 offset:22272
	ds_read_b128 v[94:97], v70 offset:23808
	s_waitcnt lgkmcnt(6)
	v_mfma_f32_32x32x16_bf16 v[34:49], v[66:69], v[98:101], 0
	ds_read_b128 v[66:69], v70 offset:24320
	s_waitcnt lgkmcnt(6)
	v_mfma_f32_32x32x16_bf16 v[34:49], v[74:77], v[102:105], v[34:49]
	s_waitcnt lgkmcnt(5)
	v_mfma_f32_32x32x16_bf16 v[50:65], v[78:81], v[98:101], 0
	s_waitcnt lgkmcnt(4)
	v_mfma_f32_32x32x16_bf16 v[50:65], v[82:85], v[102:105], v[50:65]
	s_waitcnt lgkmcnt(3)
	v_mfma_f32_32x32x16_bf16 v[34:49], v[86:89], v[106:109], v[34:49]
	s_waitcnt lgkmcnt(2)
	v_mfma_f32_32x32x16_bf16 v[50:65], v[90:93], v[106:109], v[50:65]
	s_waitcnt lgkmcnt(1)
	v_mfma_f32_32x32x16_bf16 v[34:49], v[94:97], v[110:113], v[34:49]
	s_waitcnt lgkmcnt(0)
	v_mfma_f32_32x32x16_bf16 v[50:65], v[66:69], v[110:113], v[50:65]
	s_cbranch_vccnz .LBB0_1000
	ds_read_b128 v[66:69], v191 offset:8192
	ds_read_b128 v[74:77], v191 offset:12800
	ds_read_b128 v[78:81], v191 offset:8224
	ds_read_b128 v[82:85], v191 offset:12832
	ds_read_b128 v[86:89], v191 offset:8256
	ds_read_b128 v[90:93], v191 offset:12864
	ds_read_b128 v[94:97], v191 offset:8288
	s_waitcnt lgkmcnt(6)
	v_mfma_f32_32x32x16_bf16 v[2:17], v[66:69], v[150:153], v[2:17]
	ds_read_b128 v[66:69], v191 offset:12896
	s_waitcnt lgkmcnt(6)
	v_mfma_f32_32x32x16_bf16 v[18:33], v[74:77], v[150:153], v[18:33]
	s_waitcnt lgkmcnt(5)
	v_mfma_f32_32x32x16_bf16 v[2:17], v[78:81], v[142:145], v[2:17]
	s_waitcnt lgkmcnt(4)
	v_mfma_f32_32x32x16_bf16 v[18:33], v[82:85], v[142:145], v[18:33]
	s_waitcnt lgkmcnt(3)
	v_mfma_f32_32x32x16_bf16 v[2:17], v[86:89], v[146:149], v[2:17]
	s_waitcnt lgkmcnt(2)
	v_mfma_f32_32x32x16_bf16 v[18:33], v[90:93], v[146:149], v[18:33]
	s_waitcnt lgkmcnt(1)
	v_mfma_f32_32x32x16_bf16 v[2:17], v[94:97], v[138:141], v[2:17]
	s_waitcnt lgkmcnt(0)
	v_mfma_f32_32x32x16_bf16 v[18:33], v[66:69], v[138:141], v[18:33]

; #define LAS __attribute__((address_space(3)))
; #define PVS(s, pk) do { const bf16x8 a0_ = *(const LAS bf16x8*)(vb + (s) * 32), a1_ = *(const LAS bf16x8*)(vb + 32 * VT_STRIDE + (s) * 32); \
;             o0 = __builtin_amdgcn_mfma_f32_32x32x16_bf16(a0_, pk, o0, 0, 0, 0); o1 = __builtin_amdgcn_mfma_f32_32x32x16_bf16(a1_, pk, o1, 0, 0, 0); } while (0)
; #define PVS(s, pk) do { const bf16x8 a0_ = *(const LAS bf16x8*)(vb + (s) * 32), a1_ = *(const LAS bf16x8*)(vb + 32 * VT_STRIDE + (s) * 32); \
;             o0 = __builtin_amdgcn_mfma_f32_32x32x16_bf16(a0_, pk, o0, 0, 0, 0); o1 = __builtin_amdgcn_mfma_f32_32x32x16_bf16(a1_, pk, o1, 0, 0, 0); } while (0)
; #define PVS(s, pk) do { const bf16x8 a0_ = *(const LAS bf16x8*)(vb + (s) * 32), a1_ = *(const LAS bf16x8*)(vb + 32 * VT_STRIDE + (s) * 32); \
;             o0 = __builtin_amdgcn_mfma_f32_32x32x16_bf16(a0_, pk, o0, 0, 0, 0); o1 = __builtin_amdgcn_mfma_f32_32x32x16_bf16(a1_, pk, o1, 0, 0, 0); } while (0)
; #define PVS(s, pk) do { const bf16x8 a0_ = *(const LAS bf16x8*)(vb + (s) * 32), a1_ = *(const LAS bf16x8*)(vb + 32 * VT_STRIDE + (s) * 32); \
;             o0 = __builtin_amdgcn_mfma_f32_32x32x16_bf16(a0_, pk, o0, 0, 0, 0); o1 = __builtin_amdgcn_mfma_f32_32x32x16_bf16(a1_, pk, o1, 0, 0, 0); } while (0)
; template <int MODE>
; __device__ __forceinline__ void attn_unit(LAS unsigned char* lds, const AttnArgs& A, int qb) {
;     ...
;         else if (MODE == M_MOBA) active = (i < 4) ? (key0 <= w0 + 31) : (((wmask >> ((i - 4) >> 2)) & 1ull) != 0ull);
;         else active = key0 <= w0 + 31;
;         if (active) {
;             f32x16 p0, p1;
; #pragma unroll
;             for (int r = 0; r < 16; ++r) { p0[r] = 0.f; p1[r] = 0.f; }
;             LAS unsigned char* kb = buf + kperm * 16 + hi * 1024;
; #pragma unroll
;             for (int d0 = 0; d0 < 4; ++d0) {
;                 const bf16x8 kf0 = *(const LAS bf16x8*)(kb + d0 * 2048), kf1 = *(const LAS bf16x8*)(kb + d0 * 2048 + 512);
;                 p0 = __builtin_amdgcn_mfma_f32_32x32x16_bf16(kf0, qr[d0], p0, 0, 0, 0);
;                 p1 = __builtin_amdgcn_mfma_f32_32x32x16_bf16(kf1, qr[d0], p1, 0, 0, 0);
;             }
;         if (prev_active) {
;             const LAS unsigned char* vb = lds + prevbuf + KB_BYTES + r32 * VT_STRIDE + hi * 16;
;     ...
;             PVS(0, pkP0); PVS(1, pkP1); PVS(2, pkP2); PVS(3, pkP3);
;     ...
;         }
.LBB0_1026:
	s_andn2_b64 vcc, exec, s[28:29]
	s_cbranch_vccnz .LBB0_1032
	v_add_u32_e32 v70, v186, v187
	s_nop 4
	s_nop 1
	s_and_b64 vcc, exec, s[10:11]
	ds_read_b128 v[66:69], v70 offset:35328
	ds_read_b128 v[74:77], v70 offset:37376
	ds_read_b128 v[78:81], v70 offset:35840
	ds_read_b128 v[82:85], v70 offset:37888
	ds_read_b128 v[86:89], v70 offset:39424
	ds_read_b128 v[90:93], v70 offset:39936
	ds_read_b128 v[94:97], v70 offset:41472
	s_waitcnt lgkmcnt(6)
	v_mfma_f32_32x32x16_bf16 v[34:49], v[66:69], v[98:101], 0
	ds_read_b128 v[66:69], v70 offset:41984
	s_waitcnt lgkmcnt(6)
	v_mfma_f32_32x32x16_bf16 v[34:49], v[74:77], v[102:105], v[34:49]
	s_waitcnt lgkmcnt(5)
	v_mfma_f32_32x32x16_bf16 v[50:65], v[78:81], v[98:101], 0
	s_waitcnt lgkmcnt(4)
	v_mfma_f32_32x32x16_bf16 v[50:65], v[82:85], v[102:105], v[50:65]
	s_waitcnt lgkmcnt(3)
	v_mfma_f32_32x32x16_bf16 v[34:49], v[86:89], v[106:109], v[34:49]
	s_waitcnt lgkmcnt(2)
	v_mfma_f32_32x32x16_bf16 v[50:65], v[90:93], v[106:109], v[50:65]
	s_waitcnt lgkmcnt(1)
	v_mfma_f32_32x32x16_bf16 v[34:49], v[94:97], v[110:113], v[34:49]
	s_waitcnt lgkmcnt(0)
	v_mfma_f32_32x32x16_bf16 v[50:65], v[66:69], v[110:113], v[50:65]
	s_cbranch_vccnz .LBB0_1029
	v_add_u32_e32 v70, s2, v191
	ds_read_b128 v[66:69], v70 offset:8192
	ds_read_b128 v[74:77], v70 offset:12800
	ds_read_b128 v[78:81], v70 offset:8224
	ds_read_b128 v[82:85], v70 offset:12832
	ds_read_b128 v[86:89], v70 offset:8256
	ds_read_b128 v[90:93], v70 offset:12864
	ds_read_b128 v[94:97], v70 offset:8288
	s_waitcnt lgkmcnt(6)
	v_mfma_f32_32x32x16_bf16 v[2:17], v[66:69], v[150:153], v[2:17]
	ds_read_b128 v[66:69], v70 offset:12896
	s_waitcnt lgkmcnt(6)
	v_mfma_f32_32x32x16_bf16 v[18:33], v[74:77], v[150:153], v[18:33]
	s_waitcnt lgkmcnt(5)
	v_mfma_f32_32x32x16_bf16 v[2:17], v[78:81], v[142:145], v[2:17]
	s_waitcnt lgkmcnt(4)
	v_mfma_f32_32x32x16_bf16 v[18:33], v[82:85], v[142:145], v[18:33]
	s_waitcnt lgkmcnt(3)
	v_mfma_f32_32x32x16_bf16 v[2:17], v[86:89], v[146:149], v[2:17]
	s_waitcnt lgkmcnt(2)
	v_mfma_f32_32x32x16_bf16 v[18:33], v[90:93], v[146:149], v[18:33]
	s_waitcnt lgkmcnt(1)
	v_mfma_f32_32x32x16_bf16 v[2:17], v[94:97], v[138:141], v[2:17]
	s_waitcnt lgkmcnt(0)
	v_mfma_f32_32x32x16_bf16 v[18:33], v[66:69], v[138:141], v[18:33]
